# code placement: steady-state PEER selection code shifted by 4 bytes, gather loop unchanged
# speedup vs baseline: 1.0017x; 1.0017x over previous
.LBB0_786:
	v_lshrrev_b32_e32 v2, 12, v4
	v_add_u32_e32 v2, 1, v2
	v_cndmask_b32_e64 v4, v2, 0, s[10:11]
	s_add_u32 s10, s36, 0x12684000
	v_lshl_add_u64 v[0:1], s[36:37], 0, v[0:1]
	s_addc_u32 s11, s37, 0
	v_lshl_add_u64 v[62:63], v[0:1], 0, s[96:97]
	v_add_u32_e32 v2, s60, v4
	v_mov_b64_e32 v[0:1], s[10:11]
	v_mad_u64_u32 v[2:3], s[10:11], v2, s41, v[0:1]
	s_mov_b64 s[10:11], 0xa000
	s_nop 0
	v_lshl_add_u64 v[64:65], v[2:3], 0, s[10:11]
	s_add_u32 s12, s36, s24
	v_add_u32_e32 v2, s48, v4
	s_addc_u32 s13, s37, s25
	v_mad_u64_u32 v[40:41], s[36:37], v2, s41, v[0:1]
	v_and_b32_e32 v0, 60, v232
	s_movk_i32 s36, 0xff80
	v_and_or_b32 v54, v224, s36, v0
	v_ashrrev_i32_e32 v55, 31, v54
	v_lshlrev_b64 v[60:61], 2, v[54:55]
	v_lshl_add_u64 v[4:5], v[64:65], 0, v[60:61]
	v_add_u32_e32 v34, 0x400, v54
	v_lshl_add_u64 v[26:27], v[62:63], 0, v[60:61]
	global_load_dwordx4 v[4:7], v[4:5], off
	v_ashrrev_i32_e32 v35, 31, v34
	global_load_dwordx4 v[0:3], v[26:27], off
	v_or_b32_e32 v56, 64, v54
	v_lshlrev_b64 v[50:51], 2, v[34:35]
	v_ashrrev_i32_e32 v57, 31, v56
	v_lshl_add_u64 v[34:35], v[62:63], 0, v[50:51]
	v_lshl_add_u64 v[44:45], v[64:65], 0, v[50:51]
	s_waitcnt lgkmcnt(0)
	v_lshl_add_u64 v[12:13], v[56:57], 2, v[64:65]
	global_load_dwordx4 v[34:37], v[34:35], off
	v_add_u32_e32 v58, 0x200, v54
	global_load_dwordx4 v[74:77], v[44:45], off
	v_add_u32_e32 v44, 0x440, v54
	global_load_dwordx4 v[12:15], v[12:13], off
	v_ashrrev_i32_e32 v45, 31, v44
	global_load_dwordx4 v[8:11], v[26:27], off offset:256
	global_load_dwordx4 v[18:21], v[26:27], off offset:2048
	v_lshlrev_b64 v[48:49], 2, v[44:45]
	v_ashrrev_i32_e32 v59, 31, v58
	v_lshl_add_u64 v[44:45], v[62:63], 0, v[48:49]
	v_lshl_add_u64 v[22:23], v[58:59], 2, v[64:65]
	global_load_dwordx4 v[78:81], v[44:45], off
	v_lshl_add_u64 v[44:45], v[64:65], 0, v[48:49]
	global_load_dwordx4 v[22:25], v[22:23], off
	v_add_u32_e32 v52, 0x240, v54
	global_load_dwordx4 v[70:73], v[44:45], off
	v_add_u32_e32 v44, 0x600, v54
	v_ashrrev_i32_e32 v45, 31, v44
	v_ashrrev_i32_e32 v53, 31, v52
	v_lshlrev_b64 v[46:47], 2, v[44:45]
	v_lshl_add_u64 v[30:31], v[52:53], 2, v[64:65]
	v_lshl_add_u64 v[44:45], v[62:63], 0, v[46:47]
	global_load_dwordx4 v[26:29], v[26:27], off offset:2304
	s_add_u32 s10, s12, 0x1272b180
	global_load_dwordx4 v[30:33], v[30:31], off
	s_addc_u32 s11, s13, 0
	global_load_dwordx4 v[82:85], v[44:45], off
	v_lshl_add_u64 v[44:45], v[64:65], 0, v[46:47]
	global_load_dwordx4 v[66:69], v[44:45], off
	v_add_u32_e32 v44, 0x640, v54
	v_ashrrev_i32_e32 v45, 31, v44
	v_lshlrev_b64 v[44:45], 2, v[44:45]
	v_lshl_add_u64 v[62:63], v[62:63], 0, v[44:45]
	global_load_dwordx4 v[86:89], v[62:63], off
	v_lshl_add_u64 v[62:63], v[64:65], 0, v[44:45]
	global_load_dwordx4 v[62:65], v[62:63], off
	s_add_u32 s12, s12, 0x1273b180
	s_addc_u32 s13, s13, 0
	s_mov_b64 s[0:1], 0x2000
	v_lshl_add_u64 v[42:43], v[40:41], 0, s[0:1]
	s_waitcnt vmcnt(15)
	v_pk_mul_f32 v[4:5], v[118:119], v[4:5]
	v_pk_mul_f32 v[6:7], v[120:121], v[6:7]
	s_waitcnt vmcnt(14)
	v_pk_fma_f32 v[0:1], v[0:1], s[86:87], v[4:5] op_sel_hi:[1,0,1]
	v_pk_fma_f32 v[2:3], v[2:3], s[86:87], v[6:7] op_sel_hi:[1,0,1]
	v_add_f32_e32 v4, 0, v0
	v_add_f32_e32 v4, v1, v4
	v_add_f32_e32 v4, v2, v4
	v_add_f32_e32 v4, v3, v4
	s_waitcnt vmcnt(12)
	v_pk_mul_f32 v[74:75], v[138:139], v[74:75]
	s_nop 0
	v_pk_fma_f32 v[34:35], v[34:35], s[86:87], v[74:75] op_sel_hi:[1,0,1]
	s_waitcnt vmcnt(11)
	v_pk_mul_f32 v[12:13], v[122:123], v[12:13]
	v_pk_mul_f32 v[14:15], v[124:125], v[14:15]
	s_waitcnt vmcnt(10)
	v_pk_fma_f32 v[12:13], v[8:9], s[86:87], v[12:13] op_sel_hi:[1,0,1]
	v_pk_fma_f32 v[14:15], v[10:11], s[86:87], v[14:15] op_sel_hi:[1,0,1]
	v_add_f32_e32 v4, v12, v4
	v_add_f32_e32 v4, v13, v4
	v_add_f32_e32 v4, v14, v4
	v_add_f32_e32 v4, v15, v4
	v_pk_mul_f32 v[76:77], v[140:141], v[76:77]
	s_waitcnt vmcnt(7)
	v_pk_mul_f32 v[22:23], v[126:127], v[22:23]
	s_nop 0
	v_pk_fma_f32 v[18:19], v[18:19], s[86:87], v[22:23] op_sel_hi:[1,0,1]
	v_pk_mul_f32 v[24:25], v[128:129], v[24:25]
	v_add_f32_e32 v4, v18, v4
	v_pk_fma_f32 v[24:25], v[20:21], s[86:87], v[24:25] op_sel_hi:[1,0,1]
	v_add_f32_e32 v4, v19, v4
	v_add_f32_e32 v4, v24, v4
	v_add_f32_e32 v4, v25, v4
	v_pk_fma_f32 v[36:37], v[36:37], s[86:87], v[76:77] op_sel_hi:[1,0,1]
	s_waitcnt vmcnt(6)
	v_pk_mul_f32 v[72:73], v[144:145], v[72:73]
	v_lshl_add_u64 v[20:21], s[10:11], 0, v[60:61]
	s_waitcnt vmcnt(4)
	v_pk_mul_f32 v[30:31], v[134:135], v[30:31]
	v_pk_mul_f32 v[32:33], v[136:137], v[32:33]
	v_pk_fma_f32 v[26:27], v[26:27], s[86:87], v[30:31] op_sel_hi:[1,0,1]
	v_pk_fma_f32 v[28:29], v[28:29], s[86:87], v[32:33] op_sel_hi:[1,0,1]
	v_add_f32_e32 v4, v26, v4
	v_add_f32_e32 v4, v27, v4
	v_add_f32_e32 v4, v28, v4
	v_add_f32_e32 v4, v29, v4
	v_add_f32_e32 v4, v34, v4
	s_waitcnt vmcnt(2)
	v_pk_mul_f32 v[68:69], v[152:153], v[68:69]
	v_add_f32_e32 v4, v35, v4
	s_waitcnt vmcnt(0)
	v_pk_mul_f32 v[64:65], v[132:133], v[64:65]
	v_pk_mul_f32 v[90:91], v[130:131], v[62:63]
	v_pk_fma_f32 v[62:63], v[88:89], s[86:87], v[64:65] op_sel_hi:[1,0,1]
	v_pk_fma_f32 v[64:65], v[86:87], s[86:87], v[90:91] op_sel_hi:[1,0,1]
	v_pk_mul_f32 v[86:87], v[150:151], v[66:67]
	v_pk_fma_f32 v[66:67], v[84:85], s[86:87], v[68:69] op_sel_hi:[1,0,1]
	v_pk_fma_f32 v[68:69], v[82:83], s[86:87], v[86:87] op_sel_hi:[1,0,1]
	v_pk_mul_f32 v[82:83], v[142:143], v[70:71]
	v_add_f32_e32 v4, v36, v4
	v_pk_fma_f32 v[70:71], v[80:81], s[86:87], v[72:73] op_sel_hi:[1,0,1]
	v_pk_fma_f32 v[72:73], v[78:79], s[86:87], v[82:83] op_sel_hi:[1,0,1]
	v_add_f32_e32 v4, v37, v4
	v_add_f32_e32 v4, v72, v4
	v_add_f32_e32 v4, v73, v4
	v_add_f32_e32 v4, v70, v4
	v_add_f32_e32 v4, v71, v4
	v_add_f32_e32 v4, v68, v4
	v_add_f32_e32 v4, v69, v4
	v_add_f32_e32 v4, v66, v4
	v_add_f32_e32 v4, v67, v4
	v_add_f32_e32 v4, v64, v4
	v_add_f32_e32 v4, v65, v4
	v_add_f32_e32 v4, v62, v4
	v_add_f32_e32 v4, v63, v4
	v_lshl_add_u64 v[22:23], s[12:13], 0, v[60:61]
	global_load_dwordx4 v[8:11], v[20:21], off
	global_load_dwordx4 v[84:87], v[22:23], off
	s_waitcnt lgkmcnt(0)
	v_mov_b32_e32 v5, v4
	s_nop 1
	v_permlane32_swap_b32_e32 v5, v4
	v_add_f32_e32 v4, v4, v5
	v_mov_b32_e32 v5, v4
	s_nop 1
	v_permlane16_swap_b32_e32 v5, v4
	v_add_f32_e32 v4, v4, v5
	s_nop 1
	v_add_f32_dpp v4, v4, v4 row_ror:8 row_mask:0xf bank_mask:0xf
	s_nop 1
	v_add_f32_dpp v4, v4, v4 row_ror:4 row_mask:0xf bank_mask:0xf
	s_nop 1
	v_add_f32_dpp v4, v4, v4 row_ror:2 row_mask:0xf bank_mask:0xf
	s_nop 1
	v_add_f32_dpp v4, v4, v4 row_ror:1 row_mask:0xf bank_mask:0xf
	global_load_dwordx4 v[102:105], v[20:21], off offset:256
	global_load_dwordx4 v[166:169], v[22:23], off offset:256
	global_load_dwordx4 v[106:109], v[20:21], off offset:2048
	global_load_dwordx4 v[170:173], v[22:23], off offset:2048
	global_load_dwordx4 v[110:113], v[20:21], off offset:2304
	global_load_dwordx4 v[174:177], v[22:23], off offset:2304
	v_lshl_add_u64 v[182:183], s[10:11], 0, v[50:51]
	v_lshl_add_u64 v[184:185], s[12:13], 0, v[50:51]
	global_load_dwordx4 v[114:117], v[182:183], off
	global_load_dwordx4 v[196:199], v[184:185], off
	v_lshl_add_u64 v[182:183], s[10:11], 0, v[48:49]
	v_lshl_add_u64 v[184:185], s[12:13], 0, v[48:49]
	global_load_dwordx4 v[154:157], v[182:183], off
	global_load_dwordx4 v[200:203], v[184:185], off
	v_lshl_add_u64 v[182:183], s[10:11], 0, v[46:47]
	v_lshl_add_u64 v[184:185], s[12:13], 0, v[46:47]
	global_load_dwordx4 v[158:161], v[182:183], off
	global_load_dwordx4 v[204:207], v[184:185], off
	v_lshl_add_u64 v[182:183], s[10:11], 0, v[44:45]
	v_lshl_add_u64 v[184:185], s[12:13], 0, v[44:45]
	global_load_dwordx4 v[162:165], v[182:183], off
	global_load_dwordx4 v[208:211], v[184:185], off
	v_lshl_add_u64 v[182:183], v[42:43], 0, v[60:61]
	v_lshl_add_u64 v[184:185], v[40:41], 0, v[60:61]
	global_load_dwordx4 v[234:237], v[182:183], off
	global_load_dwordx4 v[246:249], v[184:185], off
	global_load_dwordx4 v[238:241], v[182:183], off offset:256
	global_load_dwordx4 v[250:253], v[184:185], off offset:256
	global_load_dwordx4 v[242:245], v[182:183], off offset:2048
	global_load_dwordx4 v[146:149], v[184:185], off offset:2048
	v_mul_f32_e32 v6, 0x3a000000, v4
	v_pk_add_f32 v[0:1], v[0:1], v[6:7] op_sel_hi:[1,0] neg_lo:[0,1] neg_hi:[0,1]
	v_pk_add_f32 v[2:3], v[2:3], v[6:7] op_sel_hi:[1,0] neg_lo:[0,1] neg_hi:[0,1]
	v_pk_mul_f32 v[88:89], v[0:1], v[0:1]
	v_pk_mul_f32 v[90:91], v[2:3], v[2:3]
	v_add_f32_e32 v17, v88, v89
	v_pk_add_f32 v[80:81], v[12:13], v[6:7] op_sel_hi:[1,0] neg_lo:[0,1] neg_hi:[0,1]
	v_add_f32_e32 v17, v90, v17
	v_pk_mul_f32 v[92:93], v[80:81], v[80:81]
	v_add_f32_e32 v17, v91, v17
	v_pk_add_f32 v[82:83], v[14:15], v[6:7] op_sel_hi:[1,0] neg_lo:[0,1] neg_hi:[0,1]
	v_add_f32_e32 v17, v92, v17
	v_pk_mul_f32 v[94:95], v[82:83], v[82:83]
	v_add_f32_e32 v17, v93, v17
	v_pk_add_f32 v[76:77], v[18:19], v[6:7] op_sel_hi:[1,0] neg_lo:[0,1] neg_hi:[0,1]
	v_add_f32_e32 v17, v94, v17
	v_pk_mul_f32 v[18:19], v[76:77], v[76:77]
	v_add_f32_e32 v17, v95, v17
	v_pk_add_f32 v[78:79], v[24:25], v[6:7] op_sel_hi:[1,0] neg_lo:[0,1] neg_hi:[0,1]
	v_add_f32_e32 v17, v18, v17
	v_pk_mul_f32 v[96:97], v[78:79], v[78:79]
	v_add_f32_e32 v17, v19, v17
	v_pk_add_f32 v[32:33], v[26:27], v[6:7] op_sel_hi:[1,0] neg_lo:[0,1] neg_hi:[0,1]
	v_add_f32_e32 v17, v96, v17
	v_pk_mul_f32 v[98:99], v[32:33], v[32:33]
	v_add_f32_e32 v17, v97, v17
	v_pk_add_f32 v[74:75], v[28:29], v[6:7] op_sel_hi:[1,0] neg_lo:[0,1] neg_hi:[0,1]
	v_add_f32_e32 v17, v98, v17
	v_pk_mul_f32 v[100:101], v[74:75], v[74:75]
	v_add_f32_e32 v17, v99, v17
	v_pk_add_f32 v[30:31], v[34:35], v[6:7] op_sel_hi:[1,0] neg_lo:[0,1] neg_hi:[0,1]
	v_add_f32_e32 v17, v100, v17
	v_pk_mul_f32 v[34:35], v[30:31], v[30:31]
	v_add_f32_e32 v17, v101, v17
	v_pk_add_f32 v[28:29], v[36:37], v[6:7] op_sel_hi:[1,0] neg_lo:[0,1] neg_hi:[0,1]
	v_add_f32_e32 v17, v34, v17
	v_pk_mul_f32 v[36:37], v[28:29], v[28:29]
	v_add_f32_e32 v17, v35, v17
	v_pk_add_f32 v[26:27], v[72:73], v[6:7] op_sel_hi:[1,0] neg_lo:[0,1] neg_hi:[0,1]
	v_add_f32_e32 v17, v36, v17
	v_pk_mul_f32 v[72:73], v[26:27], v[26:27]
	v_add_f32_e32 v17, v37, v17
	v_pk_add_f32 v[24:25], v[70:71], v[6:7] op_sel_hi:[1,0] neg_lo:[0,1] neg_hi:[0,1]
	v_add_f32_e32 v17, v72, v17
	v_pk_mul_f32 v[70:71], v[24:25], v[24:25]
	v_add_f32_e32 v17, v73, v17
	v_pk_add_f32 v[14:15], v[68:69], v[6:7] op_sel_hi:[1,0] neg_lo:[0,1] neg_hi:[0,1]
	v_add_f32_e32 v17, v70, v17
	v_pk_mul_f32 v[68:69], v[14:15], v[14:15]
	v_add_f32_e32 v17, v71, v17
	v_pk_add_f32 v[12:13], v[66:67], v[6:7] op_sel_hi:[1,0] neg_lo:[0,1] neg_hi:[0,1]
	v_add_f32_e32 v17, v68, v17
	v_pk_mul_f32 v[66:67], v[12:13], v[12:13]
	v_add_f32_e32 v17, v69, v17
	v_pk_add_f32 v[4:5], v[64:65], v[6:7] op_sel_hi:[1,0] neg_lo:[0,1] neg_hi:[0,1]
	v_add_f32_e32 v17, v66, v17
	v_pk_mul_f32 v[64:65], v[4:5], v[4:5]
	v_add_f32_e32 v17, v67, v17
	v_pk_add_f32 v[6:7], v[62:63], v[6:7] op_sel_hi:[1,0] neg_lo:[0,1] neg_hi:[0,1]
	v_add_f32_e32 v17, v64, v17
	v_pk_mul_f32 v[62:63], v[6:7], v[6:7]
	v_add_f32_e32 v17, v65, v17
	v_add_f32_e32 v17, v62, v17
	v_add_f32_e32 v17, v63, v17
	s_waitcnt lgkmcnt(0)
	v_mov_b32_e32 v18, v17
	s_nop 1
	v_permlane32_swap_b32_e32 v18, v17
	v_add_f32_e32 v17, v17, v18
	v_mov_b32_e32 v18, v17
	s_nop 1
	v_permlane16_swap_b32_e32 v18, v17
	v_add_f32_e32 v17, v17, v18
	s_nop 1
	v_add_f32_dpp v17, v17, v17 row_ror:8 row_mask:0xf bank_mask:0xf
	s_nop 1
	v_add_f32_dpp v17, v17, v17 row_ror:4 row_mask:0xf bank_mask:0xf
	s_nop 1
	v_add_f32_dpp v17, v17, v17 row_ror:2 row_mask:0xf bank_mask:0xf
	s_nop 1
	v_add_f32_dpp v17, v17, v17 row_ror:1 row_mask:0xf bank_mask:0xf
	v_fmamk_f32 v17, v17, 0x3a000000, v186
	v_cmp_gt_f32_e32 vcc, s54, v17
	v_mul_f32_e32 v18, 0x4b800000, v17
	s_nop 0
	v_cndmask_b32_e32 v17, v17, v18, vcc
	v_rsq_f32_e32 v17, v17
	s_nop 0
	v_mul_f32_e32 v18, 0x45800000, v17
	v_cndmask_b32_e32 v18, v17, v18, vcc
	v_pk_mul_f32 v[0:1], v[0:1], v[18:19] op_sel_hi:[1,0]
	v_pk_mul_f32 v[2:3], v[2:3], v[18:19] op_sel_hi:[1,0]
	v_mov_b32_e32 v19, v18
	s_waitcnt vmcnt(0)
	v_pk_fma_f32 v[0:1], v[8:9], v[0:1], v[84:85]
	v_pk_fma_f32 v[2:3], v[10:11], v[2:3], v[86:87]
	v_lshl_add_u64 v[10:11], v[38:39], 0, v[60:61]
	v_lshl_add_u64 v[8:9], v[54:55], 1, v[178:179]
	global_store_dwordx4 v[10:11], v[0:3], off
	v_pk_mul_f32 v[80:81], v[80:81], v[18:19]
	v_pk_mul_f32 v[82:83], v[82:83], v[18:19]
	v_pk_fma_f32 v[102:103], v[80:81], v[102:103], v[166:167]
	v_pk_fma_f32 v[104:105], v[82:83], v[104:105], v[168:169]
	global_store_dwordx4 v[10:11], v[102:105], off offset:256
	v_pk_mul_f32 v[76:77], v[76:77], v[18:19]
	v_pk_mul_f32 v[78:79], v[78:79], v[18:19]
	v_pk_fma_f32 v[106:107], v[76:77], v[106:107], v[170:171]
	v_pk_fma_f32 v[108:109], v[78:79], v[108:109], v[172:173]
	global_store_dwordx4 v[10:11], v[106:109], off offset:2048
	v_pk_mul_f32 v[32:33], v[32:33], v[18:19]
	v_pk_mul_f32 v[74:75], v[74:75], v[18:19]
	v_pk_fma_f32 v[110:111], v[32:33], v[110:111], v[174:175]
	v_pk_fma_f32 v[112:113], v[74:75], v[112:113], v[176:177]
	global_store_dwordx4 v[10:11], v[110:113], off offset:2304
	v_pk_mul_f32 v[30:31], v[30:31], v[18:19]
	v_pk_mul_f32 v[28:29], v[28:29], v[18:19]
	v_pk_fma_f32 v[114:115], v[30:31], v[114:115], v[196:197]
	v_pk_fma_f32 v[116:117], v[28:29], v[116:117], v[198:199]
	v_lshl_add_u64 v[182:183], v[38:39], 0, v[50:51]
	global_store_dwordx4 v[182:183], v[114:117], off
	v_pk_mul_f32 v[26:27], v[26:27], v[18:19]
	v_pk_mul_f32 v[24:25], v[24:25], v[18:19]
	v_pk_fma_f32 v[154:155], v[26:27], v[154:155], v[200:201]
	v_pk_fma_f32 v[156:157], v[24:25], v[156:157], v[202:203]
	v_lshl_add_u64 v[182:183], v[38:39], 0, v[48:49]
	global_store_dwordx4 v[182:183], v[154:157], off
	v_pk_mul_f32 v[14:15], v[14:15], v[18:19]
	v_pk_mul_f32 v[12:13], v[12:13], v[18:19]
	v_pk_fma_f32 v[158:159], v[14:15], v[158:159], v[204:205]
	v_pk_fma_f32 v[160:161], v[12:13], v[160:161], v[206:207]
	v_lshl_add_u64 v[182:183], v[38:39], 0, v[46:47]
	global_store_dwordx4 v[182:183], v[158:161], off
	v_pk_mul_f32 v[4:5], v[4:5], v[18:19]
	v_pk_mul_f32 v[6:7], v[6:7], v[18:19]
	v_pk_fma_f32 v[162:163], v[4:5], v[162:163], v[208:209]
	v_pk_fma_f32 v[164:165], v[6:7], v[164:165], v[210:211]
	v_lshl_add_u64 v[182:183], v[38:39], 0, v[44:45]
	global_store_dwordx4 v[182:183], v[162:165], off
	s_and_b64 vcc, exec, s[4:5]
	s_cbranch_vccnz .LBB0_731
	v_lshl_add_u64 v[182:183], v[42:43], 0, v[60:61]
	v_lshl_add_u64 v[184:185], v[40:41], 0, v[60:61]
	global_load_dwordx4 v[166:169], v[182:183], off offset:2304
	global_load_dwordx4 v[204:207], v[184:185], off offset:2304
	v_lshl_add_u64 v[182:183], v[42:43], 0, v[50:51]
	v_lshl_add_u64 v[184:185], v[40:41], 0, v[50:51]
	global_load_dwordx4 v[170:173], v[182:183], off
	global_load_dwordx4 v[208:211], v[184:185], off
	v_lshl_add_u64 v[182:183], v[42:43], 0, v[48:49]
	v_lshl_add_u64 v[184:185], v[40:41], 0, v[48:49]
	global_load_dwordx4 v[174:177], v[182:183], off
	global_load_dwordx4 v[28:31], v[184:185], off
	v_lshl_add_u64 v[182:183], v[42:43], 0, v[46:47]
	v_lshl_add_u64 v[184:185], v[40:41], 0, v[46:47]
	global_load_dwordx4 v[196:199], v[182:183], off
	global_load_dwordx4 v[24:27], v[184:185], off
	v_lshl_add_u64 v[182:183], v[42:43], 0, v[44:45]
	v_lshl_add_u64 v[184:185], v[40:41], 0, v[44:45]
	global_load_dwordx4 v[200:203], v[182:183], off
	global_load_dwordx4 v[12:15], v[184:185], off
	v_pk_add_f32 v[234:235], v[234:235], 1.0 op_sel_hi:[1,0]
	v_pk_add_f32 v[236:237], v[236:237], 1.0 op_sel_hi:[1,0]
	v_pk_fma_f32 v[0:1], v[0:1], v[234:235], v[246:247]
	v_pk_fma_f32 v[2:3], v[2:3], v[236:237], v[248:249]
	v_cvt_pk_bf16_f32 v0, v0, v1
	v_cvt_pk_bf16_f32 v1, v2, v3
	global_store_dwordx2 v[8:9], v[0:1], off
	v_pk_add_f32 v[238:239], v[238:239], 1.0 op_sel_hi:[1,0]
	v_pk_add_f32 v[240:241], v[240:241], 1.0 op_sel_hi:[1,0]
	v_pk_fma_f32 v[102:103], v[102:103], v[238:239], v[250:251]
	v_pk_fma_f32 v[104:105], v[104:105], v[240:241], v[252:253]
	v_cvt_pk_bf16_f32 v102, v102, v103
	v_cvt_pk_bf16_f32 v103, v104, v105
	global_store_dwordx2 v[8:9], v[102:103], off offset:128
	v_pk_add_f32 v[242:243], v[242:243], 1.0 op_sel_hi:[1,0]
	v_pk_add_f32 v[244:245], v[244:245], 1.0 op_sel_hi:[1,0]
	v_pk_fma_f32 v[106:107], v[106:107], v[242:243], v[146:147]
	v_pk_fma_f32 v[108:109], v[108:109], v[244:245], v[148:149]
	v_cvt_pk_bf16_f32 v106, v106, v107
	v_cvt_pk_bf16_f32 v107, v108, v109
	global_store_dwordx2 v[8:9], v[106:107], off offset:1024
	s_waitcnt vmcnt(3)
	v_pk_add_f32 v[166:167], v[166:167], 1.0 op_sel_hi:[1,0]
	v_pk_add_f32 v[168:169], v[168:169], 1.0 op_sel_hi:[1,0]
	v_pk_fma_f32 v[110:111], v[110:111], v[166:167], v[204:205]
	v_pk_fma_f32 v[112:113], v[112:113], v[168:169], v[206:207]
	v_cvt_pk_bf16_f32 v110, v110, v111
	v_cvt_pk_bf16_f32 v111, v112, v113
	global_store_dwordx2 v[8:9], v[110:111], off offset:1152
	v_pk_add_f32 v[170:171], v[170:171], 1.0 op_sel_hi:[1,0]
	v_pk_add_f32 v[172:173], v[172:173], 1.0 op_sel_hi:[1,0]
	v_pk_fma_f32 v[114:115], v[114:115], v[170:171], v[208:209]
	v_pk_fma_f32 v[116:117], v[116:117], v[172:173], v[210:211]
	v_cvt_pk_bf16_f32 v114, v114, v115
	v_cvt_pk_bf16_f32 v115, v116, v117
	global_store_dwordx2 v[8:9], v[114:115], off offset:2048
	v_pk_add_f32 v[174:175], v[174:175], 1.0 op_sel_hi:[1,0]
	v_pk_add_f32 v[176:177], v[176:177], 1.0 op_sel_hi:[1,0]
	v_pk_fma_f32 v[154:155], v[154:155], v[174:175], v[28:29]
	v_pk_fma_f32 v[156:157], v[156:157], v[176:177], v[30:31]
	v_cvt_pk_bf16_f32 v154, v154, v155
	v_cvt_pk_bf16_f32 v155, v156, v157
	global_store_dwordx2 v[8:9], v[154:155], off offset:2176
	v_pk_add_f32 v[196:197], v[196:197], 1.0 op_sel_hi:[1,0]
	v_pk_add_f32 v[198:199], v[198:199], 1.0 op_sel_hi:[1,0]
	v_pk_fma_f32 v[158:159], v[158:159], v[196:197], v[24:25]
	v_pk_fma_f32 v[160:161], v[160:161], v[198:199], v[26:27]
	v_cvt_pk_bf16_f32 v158, v158, v159
	v_cvt_pk_bf16_f32 v159, v160, v161
	global_store_dwordx2 v[8:9], v[158:159], off offset:3072
	v_pk_add_f32 v[200:201], v[200:201], 1.0 op_sel_hi:[1,0]
	v_pk_add_f32 v[202:203], v[202:203], 1.0 op_sel_hi:[1,0]
	v_pk_fma_f32 v[162:163], v[162:163], v[200:201], v[12:13]
	v_pk_fma_f32 v[164:165], v[164:165], v[202:203], v[14:15]
	v_cvt_pk_bf16_f32 v162, v162, v163
	v_cvt_pk_bf16_f32 v163, v164, v165
	global_store_dwordx2 v[8:9], v[162:163], off offset:3200
	s_branch .LBB0_731
	s_nop 0
